# P0 weight transposes: all 32 tile loads in flight before the first wait (was 4 serial rounds of 8)
# baseline (speedup 1.0000x reference)
.LBB0_19:
	v_lshl_add_u64 v[66:67], v[52:53], 0, s[4:5]
	v_lshl_add_u64 v[68:69], v[50:51], 0, s[4:5]
	v_lshl_add_u64 v[70:71], v[48:49], 0, s[4:5]
	v_lshl_add_u64 v[72:73], v[46:47], 0, s[4:5]
	v_lshl_add_u64 v[74:75], v[44:45], 0, s[4:5]
	v_lshl_add_u64 v[76:77], v[42:43], 0, s[4:5]
	v_lshl_add_u64 v[78:79], v[40:41], 0, s[4:5]
	v_lshl_add_u64 v[80:81], v[38:39], 0, s[4:5]
	global_load_dword v150, v[66:67], off nt
	global_load_dword v151, v[68:69], off nt
	global_load_dword v152, v[70:71], off nt
	global_load_dword v153, v[72:73], off nt
	global_load_dword v154, v[74:75], off nt
	global_load_dword v155, v[76:77], off nt
	global_load_dword v156, v[78:79], off nt
	global_load_dword v157, v[80:81], off nt
	s_add_u32 s4, s4, 0x10000
	s_addc_u32 s5, s5, 0
	v_lshl_add_u64 v[66:67], v[52:53], 0, s[4:5]
	v_lshl_add_u64 v[68:69], v[50:51], 0, s[4:5]
	v_lshl_add_u64 v[70:71], v[48:49], 0, s[4:5]
	v_lshl_add_u64 v[72:73], v[46:47], 0, s[4:5]
	v_lshl_add_u64 v[74:75], v[44:45], 0, s[4:5]
	v_lshl_add_u64 v[76:77], v[42:43], 0, s[4:5]
	v_lshl_add_u64 v[78:79], v[40:41], 0, s[4:5]
	v_lshl_add_u64 v[80:81], v[38:39], 0, s[4:5]
	global_load_dword v158, v[66:67], off nt
	global_load_dword v159, v[68:69], off nt
	global_load_dword v160, v[70:71], off nt
	global_load_dword v161, v[72:73], off nt
	global_load_dword v162, v[74:75], off nt
	global_load_dword v163, v[76:77], off nt
	global_load_dword v164, v[78:79], off nt
	global_load_dword v165, v[80:81], off nt
	s_add_u32 s4, s4, 0x10000
	s_addc_u32 s5, s5, 0
	v_lshl_add_u64 v[66:67], v[52:53], 0, s[4:5]
	v_lshl_add_u64 v[68:69], v[50:51], 0, s[4:5]
	v_lshl_add_u64 v[70:71], v[48:49], 0, s[4:5]
	v_lshl_add_u64 v[72:73], v[46:47], 0, s[4:5]
	v_lshl_add_u64 v[74:75], v[44:45], 0, s[4:5]
	v_lshl_add_u64 v[76:77], v[42:43], 0, s[4:5]
	v_lshl_add_u64 v[78:79], v[40:41], 0, s[4:5]
	v_lshl_add_u64 v[80:81], v[38:39], 0, s[4:5]
	global_load_dword v166, v[66:67], off nt
	global_load_dword v167, v[68:69], off nt
	global_load_dword v168, v[70:71], off nt
	global_load_dword v169, v[72:73], off nt
	global_load_dword v170, v[74:75], off nt
	global_load_dword v171, v[76:77], off nt
	global_load_dword v172, v[78:79], off nt
	global_load_dword v173, v[80:81], off nt
	s_add_u32 s4, s4, 0x10000
	s_addc_u32 s5, s5, 0
	v_lshl_add_u64 v[66:67], v[52:53], 0, s[4:5]
	v_lshl_add_u64 v[68:69], v[50:51], 0, s[4:5]
	v_lshl_add_u64 v[70:71], v[48:49], 0, s[4:5]
	v_lshl_add_u64 v[72:73], v[46:47], 0, s[4:5]
	v_lshl_add_u64 v[74:75], v[44:45], 0, s[4:5]
	v_lshl_add_u64 v[76:77], v[42:43], 0, s[4:5]
	v_lshl_add_u64 v[78:79], v[40:41], 0, s[4:5]
	v_lshl_add_u64 v[80:81], v[38:39], 0, s[4:5]
	global_load_dword v174, v[66:67], off nt
	global_load_dword v175, v[68:69], off nt
	global_load_dword v176, v[70:71], off nt
	global_load_dword v177, v[72:73], off nt
	global_load_dword v178, v[74:75], off nt
	global_load_dword v179, v[76:77], off nt
	global_load_dword v180, v[78:79], off nt
	global_load_dword v181, v[80:81], off nt
	s_add_u32 s4, s4, 0x10000
	s_addc_u32 s5, s5, 0
	v_add_u32_e32 v74, 0x400, v65
	s_waitcnt vmcnt(30)
	ds_write2_b32 v65, v150, v151 offset1:66
	s_waitcnt vmcnt(28)
	ds_write2_b32 v65, v152, v153 offset0:132 offset1:198
	s_waitcnt vmcnt(26)
	ds_write2_b32 v74, v154, v155 offset0:8 offset1:74
	s_waitcnt vmcnt(24)
	ds_write2_b32 v74, v156, v157 offset0:140 offset1:206
	v_add_u32_e32 v65, 0x840, v65
	v_add_u32_e32 v74, 0x400, v65
	s_waitcnt vmcnt(22)
	ds_write2_b32 v65, v158, v159 offset1:66
	s_waitcnt vmcnt(20)
	ds_write2_b32 v65, v160, v161 offset0:132 offset1:198
	s_waitcnt vmcnt(18)
	ds_write2_b32 v74, v162, v163 offset0:8 offset1:74
	s_waitcnt vmcnt(16)
	ds_write2_b32 v74, v164, v165 offset0:140 offset1:206
	v_add_u32_e32 v65, 0x840, v65
	v_add_u32_e32 v74, 0x400, v65
	s_waitcnt vmcnt(14)
	ds_write2_b32 v65, v166, v167 offset1:66
	s_waitcnt vmcnt(12)
	ds_write2_b32 v65, v168, v169 offset0:132 offset1:198
	s_waitcnt vmcnt(10)
	ds_write2_b32 v74, v170, v171 offset0:8 offset1:74
	s_waitcnt vmcnt(8)
	ds_write2_b32 v74, v172, v173 offset0:140 offset1:206
	v_add_u32_e32 v65, 0x840, v65
	v_add_u32_e32 v74, 0x400, v65
	s_waitcnt vmcnt(6)
	ds_write2_b32 v65, v174, v175 offset1:66
	s_waitcnt vmcnt(4)
	ds_write2_b32 v65, v176, v177 offset0:132 offset1:198
	s_waitcnt vmcnt(2)
	ds_write2_b32 v74, v178, v179 offset0:8 offset1:74
	s_waitcnt vmcnt(0)
	ds_write2_b32 v74, v180, v181 offset0:140 offset1:206
	v_add_u32_e32 v65, 0x840, v65
	s_cmp_lg_u32 s4, 0x40000
	s_waitcnt lgkmcnt(0)
	ds_read2_b32 v[42:43], v17 offset1:8
	ds_read2_b32 v[46:47], v17 offset0:33 offset1:41
	ds_read2_b32 v[48:49], v17 offset0:66 offset1:74
	ds_read2_b32 v[50:51], v17 offset0:99 offset1:107
	ds_read2_b32 v[52:53], v17 offset0:132 offset1:140
	s_waitcnt lgkmcnt(4)
	v_bfe_u32 v38, v42, 16, 1
	v_add3_u32 v38, v42, v38, s23
	s_waitcnt lgkmcnt(3)
	v_bfe_u32 v39, v46, 16, 1
	v_lshrrev_b32_e32 v38, 16, v38
	v_add3_u32 v39, v46, v39, s23
	ds_read2_b32 v[66:67], v17 offset0:165 offset1:173
	v_and_or_b32 v38, v39, s24, v38
	s_waitcnt lgkmcnt(3)
	v_bfe_u32 v39, v48, 16, 1
	v_add3_u32 v39, v48, v39, s23
	s_waitcnt lgkmcnt(2)
	v_bfe_u32 v40, v50, 16, 1
	ds_read2_b32 v[68:69], v17 offset0:198 offset1:206
	v_lshrrev_b32_e32 v39, 16, v39
	v_add3_u32 v40, v50, v40, s23
	ds_read2_b32 v[70:71], v17 offset0:231 offset1:239
	v_and_or_b32 v39, v40, s24, v39
	s_waitcnt lgkmcnt(3)
	v_bfe_u32 v40, v52, 16, 1
	v_add3_u32 v40, v52, v40, s23
	s_waitcnt lgkmcnt(2)
	v_bfe_u32 v41, v66, 16, 1
	v_lshrrev_b32_e32 v40, 16, v40
	v_add3_u32 v41, v66, v41, s23
	v_and_or_b32 v40, v41, s24, v40
	s_waitcnt lgkmcnt(1)
	v_bfe_u32 v41, v68, 16, 1
	s_add_i32 s0, s9, 0x1e400
	s_lshl_b32 s4, s25, 5
	v_add3_u32 v41, v68, v41, s23
	s_waitcnt lgkmcnt(0)
	v_bfe_u32 v42, v70, 16, 1
	s_and_b32 s0, s0, 0x1ffc0
	s_and_b32 s4, s4, 0x3e0
	v_lshrrev_b32_e32 v41, 16, v41
	v_add3_u32 v42, v70, v42, s23
	s_lshl_b32 s0, s0, 1
	v_and_or_b32 v41, v42, s24, v41
	v_or_b32_e32 v42, s4, v1
	v_lshl_add_u64 v[44:45], v[4:5], 0, s[0:1]
	v_lshlrev_b32_e32 v72, 11, v42
	v_mov_b32_e32 v73, v3
	v_lshl_add_u64 v[72:73], v[44:45], 0, v[72:73]
	global_store_dwordx4 v[72:73], v[38:41], off
	v_bfe_u32 v42, v71, 16, 1
	v_add3_u32 v42, v71, v42, s23
	v_bfe_u32 v38, v43, 16, 1
	v_add3_u32 v38, v43, v38, s23
	v_bfe_u32 v39, v47, 16, 1
	v_lshrrev_b32_e32 v38, 16, v38
	v_add3_u32 v39, v47, v39, s23
	v_and_or_b32 v38, v39, s24, v38
	v_bfe_u32 v39, v49, 16, 1
	v_add3_u32 v39, v49, v39, s23
	v_bfe_u32 v40, v51, 16, 1
	v_lshrrev_b32_e32 v39, 16, v39
	v_add3_u32 v40, v51, v40, s23
	v_and_or_b32 v39, v40, s24, v39
	v_bfe_u32 v40, v53, 16, 1
	v_add3_u32 v40, v53, v40, s23
	v_bfe_u32 v41, v67, 16, 1
	v_lshrrev_b32_e32 v40, 16, v40
	v_add3_u32 v41, v67, v41, s23
	v_and_or_b32 v40, v41, s24, v40
	v_bfe_u32 v41, v69, 16, 1
	v_add3_u32 v41, v69, v41, s23
	v_lshrrev_b32_e32 v41, 16, v41
	v_and_or_b32 v41, v42, s24, v41
	v_or_b32_e32 v42, s4, v54
	v_lshlrev_b32_e32 v42, 11, v42
	v_mov_b32_e32 v43, v3
	ds_read2_b32 v[46:47], v17 offset0:16 offset1:24
	v_lshl_add_u64 v[42:43], v[44:45], 0, v[42:43]
	global_store_dwordx4 v[42:43], v[38:41], off
	ds_read2_b32 v[42:43], v17 offset0:49 offset1:57
	ds_read2_b32 v[48:49], v17 offset0:82 offset1:90
	ds_read2_b32 v[50:51], v17 offset0:115 offset1:123
	s_waitcnt lgkmcnt(3)
	v_bfe_u32 v38, v46, 16, 1
	v_add3_u32 v38, v46, v38, s23
	s_waitcnt lgkmcnt(2)
	v_bfe_u32 v39, v42, 16, 1
	ds_read2_b32 v[52:53], v17 offset0:148 offset1:156
	v_lshrrev_b32_e32 v38, 16, v38
	v_add3_u32 v39, v42, v39, s23
	ds_read2_b32 v[66:67], v17 offset0:181 offset1:189
	v_and_or_b32 v38, v39, s24, v38
	s_waitcnt lgkmcnt(3)
	v_bfe_u32 v39, v48, 16, 1
	v_add3_u32 v39, v48, v39, s23
	s_waitcnt lgkmcnt(2)
	v_bfe_u32 v40, v50, 16, 1
	ds_read2_b32 v[68:69], v17 offset0:214 offset1:222
	v_lshrrev_b32_e32 v39, 16, v39
	v_add3_u32 v40, v50, v40, s23
	ds_read2_b32 v[70:71], v17 offset0:247 offset1:255
	v_and_or_b32 v39, v40, s24, v39
	s_waitcnt lgkmcnt(3)
	v_bfe_u32 v40, v52, 16, 1
	v_add3_u32 v40, v52, v40, s23
	s_waitcnt lgkmcnt(2)
	v_bfe_u32 v41, v66, 16, 1
	v_lshrrev_b32_e32 v40, 16, v40
	v_add3_u32 v41, v66, v41, s23
	v_and_or_b32 v40, v41, s24, v40
	s_waitcnt lgkmcnt(1)
	v_bfe_u32 v41, v68, 16, 1
	v_add3_u32 v41, v68, v41, s23
	s_waitcnt lgkmcnt(0)
	v_bfe_u32 v42, v70, 16, 1
	v_lshrrev_b32_e32 v41, 16, v41
	v_add3_u32 v42, v70, v42, s23
	v_and_or_b32 v41, v42, s24, v41
	v_or_b32_e32 v42, s4, v55
	v_lshlrev_b32_e32 v72, 11, v42
	v_mov_b32_e32 v73, v3
	v_lshl_add_u64 v[72:73], v[44:45], 0, v[72:73]
	global_store_dwordx4 v[72:73], v[38:41], off
	v_bfe_u32 v42, v71, 16, 1
	v_add3_u32 v42, v71, v42, s23
	v_bfe_u32 v38, v47, 16, 1
	v_add3_u32 v38, v47, v38, s23
	v_bfe_u32 v39, v43, 16, 1
	v_lshrrev_b32_e32 v38, 16, v38
	v_add3_u32 v39, v43, v39, s23
	v_and_or_b32 v38, v39, s24, v38
	v_bfe_u32 v39, v49, 16, 1
	v_add3_u32 v39, v49, v39, s23
	v_bfe_u32 v40, v51, 16, 1
	v_lshrrev_b32_e32 v39, 16, v39
	v_add3_u32 v40, v51, v40, s23
	v_and_or_b32 v39, v40, s24, v39
	v_bfe_u32 v40, v53, 16, 1
	v_add3_u32 v40, v53, v40, s23
	v_bfe_u32 v41, v67, 16, 1
	v_lshrrev_b32_e32 v40, 16, v40
	v_add3_u32 v41, v67, v41, s23
	v_and_or_b32 v40, v41, s24, v40
	v_bfe_u32 v41, v69, 16, 1
	v_add3_u32 v41, v69, v41, s23
	v_lshrrev_b32_e32 v41, 16, v41
	v_and_or_b32 v41, v42, s24, v41
	v_add_lshl_u32 v42, s4, v56, 11
	v_mov_b32_e32 v43, v3
	v_lshl_add_u64 v[42:43], v[44:45], 0, v[42:43]
	global_store_dwordx4 v[42:43], v[38:41], off
	s_waitcnt lgkmcnt(0)
	s_mov_b64 s[4:5], 0

.LBB0_23:
	v_lshl_add_u64 v[66:67], v[52:53], 0, s[4:5]
	v_lshl_add_u64 v[68:69], v[50:51], 0, s[4:5]
	v_lshl_add_u64 v[70:71], v[48:49], 0, s[4:5]
	v_lshl_add_u64 v[72:73], v[46:47], 0, s[4:5]
	v_lshl_add_u64 v[74:75], v[44:45], 0, s[4:5]
	v_lshl_add_u64 v[76:77], v[42:43], 0, s[4:5]
	v_lshl_add_u64 v[78:79], v[40:41], 0, s[4:5]
	v_lshl_add_u64 v[80:81], v[38:39], 0, s[4:5]
	global_load_dword v150, v[66:67], off nt
	global_load_dword v151, v[68:69], off nt
	global_load_dword v152, v[70:71], off nt
	global_load_dword v153, v[72:73], off nt
	global_load_dword v154, v[74:75], off nt
	global_load_dword v155, v[76:77], off nt
	global_load_dword v156, v[78:79], off nt
	global_load_dword v157, v[80:81], off nt
	s_add_u32 s4, s4, 0x10000
	s_addc_u32 s5, s5, 0
	v_lshl_add_u64 v[66:67], v[52:53], 0, s[4:5]
	v_lshl_add_u64 v[68:69], v[50:51], 0, s[4:5]
	v_lshl_add_u64 v[70:71], v[48:49], 0, s[4:5]
	v_lshl_add_u64 v[72:73], v[46:47], 0, s[4:5]
	v_lshl_add_u64 v[74:75], v[44:45], 0, s[4:5]
	v_lshl_add_u64 v[76:77], v[42:43], 0, s[4:5]
	v_lshl_add_u64 v[78:79], v[40:41], 0, s[4:5]
	v_lshl_add_u64 v[80:81], v[38:39], 0, s[4:5]
	global_load_dword v158, v[66:67], off nt
	global_load_dword v159, v[68:69], off nt
	global_load_dword v160, v[70:71], off nt
	global_load_dword v161, v[72:73], off nt
	global_load_dword v162, v[74:75], off nt
	global_load_dword v163, v[76:77], off nt
	global_load_dword v164, v[78:79], off nt
	global_load_dword v165, v[80:81], off nt
	s_add_u32 s4, s4, 0x10000
	s_addc_u32 s5, s5, 0
	v_lshl_add_u64 v[66:67], v[52:53], 0, s[4:5]
	v_lshl_add_u64 v[68:69], v[50:51], 0, s[4:5]
	v_lshl_add_u64 v[70:71], v[48:49], 0, s[4:5]
	v_lshl_add_u64 v[72:73], v[46:47], 0, s[4:5]
	v_lshl_add_u64 v[74:75], v[44:45], 0, s[4:5]
	v_lshl_add_u64 v[76:77], v[42:43], 0, s[4:5]
	v_lshl_add_u64 v[78:79], v[40:41], 0, s[4:5]
	v_lshl_add_u64 v[80:81], v[38:39], 0, s[4:5]
	global_load_dword v166, v[66:67], off nt
	global_load_dword v167, v[68:69], off nt
	global_load_dword v168, v[70:71], off nt
	global_load_dword v169, v[72:73], off nt
	global_load_dword v170, v[74:75], off nt
	global_load_dword v171, v[76:77], off nt
	global_load_dword v172, v[78:79], off nt
	global_load_dword v173, v[80:81], off nt
	s_add_u32 s4, s4, 0x10000
	s_addc_u32 s5, s5, 0
	v_lshl_add_u64 v[66:67], v[52:53], 0, s[4:5]
	v_lshl_add_u64 v[68:69], v[50:51], 0, s[4:5]
	v_lshl_add_u64 v[70:71], v[48:49], 0, s[4:5]
	v_lshl_add_u64 v[72:73], v[46:47], 0, s[4:5]
	v_lshl_add_u64 v[74:75], v[44:45], 0, s[4:5]
	v_lshl_add_u64 v[76:77], v[42:43], 0, s[4:5]
	v_lshl_add_u64 v[78:79], v[40:41], 0, s[4:5]
	v_lshl_add_u64 v[80:81], v[38:39], 0, s[4:5]
	global_load_dword v174, v[66:67], off nt
	global_load_dword v175, v[68:69], off nt
	global_load_dword v176, v[70:71], off nt
	global_load_dword v177, v[72:73], off nt
	global_load_dword v178, v[74:75], off nt
	global_load_dword v179, v[76:77], off nt
	global_load_dword v180, v[78:79], off nt
	global_load_dword v181, v[80:81], off nt
	s_add_u32 s4, s4, 0x10000
	s_addc_u32 s5, s5, 0
	v_add_u32_e32 v74, 0x400, v65
	s_waitcnt vmcnt(30)
	ds_write2_b32 v65, v150, v151 offset1:66
	s_waitcnt vmcnt(28)
	ds_write2_b32 v65, v152, v153 offset0:132 offset1:198
	s_waitcnt vmcnt(26)
	ds_write2_b32 v74, v154, v155 offset0:8 offset1:74
	s_waitcnt vmcnt(24)
	ds_write2_b32 v74, v156, v157 offset0:140 offset1:206
	v_add_u32_e32 v65, 0x840, v65
	v_add_u32_e32 v74, 0x400, v65
	s_waitcnt vmcnt(22)
	ds_write2_b32 v65, v158, v159 offset1:66
	s_waitcnt vmcnt(20)
	ds_write2_b32 v65, v160, v161 offset0:132 offset1:198
	s_waitcnt vmcnt(18)
	ds_write2_b32 v74, v162, v163 offset0:8 offset1:74
	s_waitcnt vmcnt(16)
	ds_write2_b32 v74, v164, v165 offset0:140 offset1:206
	v_add_u32_e32 v65, 0x840, v65
	v_add_u32_e32 v74, 0x400, v65
	s_waitcnt vmcnt(14)
	ds_write2_b32 v65, v166, v167 offset1:66
	s_waitcnt vmcnt(12)
	ds_write2_b32 v65, v168, v169 offset0:132 offset1:198
	s_waitcnt vmcnt(10)
	ds_write2_b32 v74, v170, v171 offset0:8 offset1:74
	s_waitcnt vmcnt(8)
	ds_write2_b32 v74, v172, v173 offset0:140 offset1:206
	v_add_u32_e32 v65, 0x840, v65
	v_add_u32_e32 v74, 0x400, v65
	s_waitcnt vmcnt(6)
	ds_write2_b32 v65, v174, v175 offset1:66
	s_waitcnt vmcnt(4)
	ds_write2_b32 v65, v176, v177 offset0:132 offset1:198
	s_waitcnt vmcnt(2)
	ds_write2_b32 v74, v178, v179 offset0:8 offset1:74
	s_waitcnt vmcnt(0)
	ds_write2_b32 v74, v180, v181 offset0:140 offset1:206
	v_add_u32_e32 v65, 0x840, v65
	s_cmp_lg_u32 s4, 0x40000
	s_waitcnt lgkmcnt(0)
	ds_read2_b32 v[42:43], v17 offset1:8
	ds_read2_b32 v[46:47], v17 offset0:33 offset1:41
	ds_read2_b32 v[48:49], v17 offset0:66 offset1:74
	ds_read2_b32 v[50:51], v17 offset0:99 offset1:107
	ds_read2_b32 v[52:53], v17 offset0:132 offset1:140
	s_waitcnt lgkmcnt(4)
	v_bfe_u32 v38, v42, 16, 1
	v_add3_u32 v38, v42, v38, s23
	s_waitcnt lgkmcnt(3)
	v_bfe_u32 v39, v46, 16, 1
	v_lshrrev_b32_e32 v38, 16, v38
	v_add3_u32 v39, v46, v39, s23
	ds_read2_b32 v[66:67], v17 offset0:165 offset1:173
	v_and_or_b32 v38, v39, s24, v38
	s_waitcnt lgkmcnt(3)
	v_bfe_u32 v39, v48, 16, 1
	v_add3_u32 v39, v48, v39, s23
	s_waitcnt lgkmcnt(2)
	v_bfe_u32 v40, v50, 16, 1
	ds_read2_b32 v[68:69], v17 offset0:198 offset1:206
	v_lshrrev_b32_e32 v39, 16, v39
	v_add3_u32 v40, v50, v40, s23
	ds_read2_b32 v[70:71], v17 offset0:231 offset1:239
	v_and_or_b32 v39, v40, s24, v39
	s_waitcnt lgkmcnt(3)
	v_bfe_u32 v40, v52, 16, 1
	v_add3_u32 v40, v52, v40, s23
	s_waitcnt lgkmcnt(2)
	v_bfe_u32 v41, v66, 16, 1
	v_lshrrev_b32_e32 v40, 16, v40
	v_add3_u32 v41, v66, v41, s23
	v_and_or_b32 v40, v41, s24, v40
	s_waitcnt lgkmcnt(1)
	v_bfe_u32 v41, v68, 16, 1
	s_lshl_b32 s4, s25, 5
	v_add3_u32 v41, v68, v41, s23
	s_waitcnt lgkmcnt(0)
	v_bfe_u32 v42, v70, 16, 1
	s_and_b32 s0, s9, 0x1c0
	s_and_b32 s4, s4, 0x3e0
	v_lshrrev_b32_e32 v41, 16, v41
	v_add3_u32 v42, v70, v42, s23
	s_lshl_b32 s0, s0, 1
	v_and_or_b32 v41, v42, s24, v41
	v_or_b32_e32 v42, s4, v1
	v_lshl_add_u64 v[44:45], v[6:7], 0, s[0:1]
	v_lshlrev_b32_e32 v72, 11, v42
	v_mov_b32_e32 v73, v3
	v_lshl_add_u64 v[72:73], v[44:45], 0, v[72:73]
	global_store_dwordx4 v[72:73], v[38:41], off
	v_bfe_u32 v42, v71, 16, 1
	v_add3_u32 v42, v71, v42, s23
	v_bfe_u32 v38, v43, 16, 1
	v_add3_u32 v38, v43, v38, s23
	v_bfe_u32 v39, v47, 16, 1
	v_lshrrev_b32_e32 v38, 16, v38
	v_add3_u32 v39, v47, v39, s23
	v_and_or_b32 v38, v39, s24, v38
	v_bfe_u32 v39, v49, 16, 1
	v_add3_u32 v39, v49, v39, s23
	v_bfe_u32 v40, v51, 16, 1
	v_lshrrev_b32_e32 v39, 16, v39
	v_add3_u32 v40, v51, v40, s23
	v_and_or_b32 v39, v40, s24, v39
	v_bfe_u32 v40, v53, 16, 1
	v_add3_u32 v40, v53, v40, s23
	v_bfe_u32 v41, v67, 16, 1
	v_lshrrev_b32_e32 v40, 16, v40
	v_add3_u32 v41, v67, v41, s23
	v_and_or_b32 v40, v41, s24, v40
	v_bfe_u32 v41, v69, 16, 1
	v_add3_u32 v41, v69, v41, s23
	v_lshrrev_b32_e32 v41, 16, v41
	v_and_or_b32 v41, v42, s24, v41
	v_or_b32_e32 v42, s4, v54
	v_lshlrev_b32_e32 v42, 11, v42
	v_mov_b32_e32 v43, v3
	ds_read2_b32 v[46:47], v17 offset0:16 offset1:24
	v_lshl_add_u64 v[42:43], v[44:45], 0, v[42:43]
	global_store_dwordx4 v[42:43], v[38:41], off
	ds_read2_b32 v[42:43], v17 offset0:49 offset1:57
	ds_read2_b32 v[48:49], v17 offset0:82 offset1:90
	ds_read2_b32 v[50:51], v17 offset0:115 offset1:123
	s_waitcnt lgkmcnt(3)
	v_bfe_u32 v38, v46, 16, 1
	v_add3_u32 v38, v46, v38, s23
	s_waitcnt lgkmcnt(2)
	v_bfe_u32 v39, v42, 16, 1
	ds_read2_b32 v[52:53], v17 offset0:148 offset1:156
	v_lshrrev_b32_e32 v38, 16, v38
	v_add3_u32 v39, v42, v39, s23
	ds_read2_b32 v[66:67], v17 offset0:181 offset1:189
	v_and_or_b32 v38, v39, s24, v38
	s_waitcnt lgkmcnt(3)
	v_bfe_u32 v39, v48, 16, 1
	v_add3_u32 v39, v48, v39, s23
	s_waitcnt lgkmcnt(2)
	v_bfe_u32 v40, v50, 16, 1
	ds_read2_b32 v[68:69], v17 offset0:214 offset1:222
	v_lshrrev_b32_e32 v39, 16, v39
	v_add3_u32 v40, v50, v40, s23
	ds_read2_b32 v[70:71], v17 offset0:247 offset1:255
	v_and_or_b32 v39, v40, s24, v39
	s_waitcnt lgkmcnt(3)
	v_bfe_u32 v40, v52, 16, 1
	v_add3_u32 v40, v52, v40, s23
	s_waitcnt lgkmcnt(2)
	v_bfe_u32 v41, v66, 16, 1
	v_lshrrev_b32_e32 v40, 16, v40
	v_add3_u32 v41, v66, v41, s23
	v_and_or_b32 v40, v41, s24, v40
	s_waitcnt lgkmcnt(1)
	v_bfe_u32 v41, v68, 16, 1
	v_add3_u32 v41, v68, v41, s23
	s_waitcnt lgkmcnt(0)
	v_bfe_u32 v42, v70, 16, 1
	v_lshrrev_b32_e32 v41, 16, v41
	v_add3_u32 v42, v70, v42, s23
	v_and_or_b32 v41, v42, s24, v41
	v_or_b32_e32 v42, s4, v55
	v_lshlrev_b32_e32 v72, 11, v42
	v_mov_b32_e32 v73, v3
	v_lshl_add_u64 v[72:73], v[44:45], 0, v[72:73]
	global_store_dwordx4 v[72:73], v[38:41], off
	v_bfe_u32 v42, v71, 16, 1
	v_add3_u32 v42, v71, v42, s23
	v_bfe_u32 v38, v47, 16, 1
	v_add3_u32 v38, v47, v38, s23
	v_bfe_u32 v39, v43, 16, 1
	v_lshrrev_b32_e32 v38, 16, v38
	v_add3_u32 v39, v43, v39, s23
	v_and_or_b32 v38, v39, s24, v38
	v_bfe_u32 v39, v49, 16, 1
	v_add3_u32 v39, v49, v39, s23
	v_bfe_u32 v40, v51, 16, 1
	v_lshrrev_b32_e32 v39, 16, v39
	v_add3_u32 v40, v51, v40, s23
	v_and_or_b32 v39, v40, s24, v39
	v_bfe_u32 v40, v53, 16, 1
	v_add3_u32 v40, v53, v40, s23
	v_bfe_u32 v41, v67, 16, 1
	v_lshrrev_b32_e32 v40, 16, v40
	v_add3_u32 v41, v67, v41, s23
	v_and_or_b32 v40, v41, s24, v40
	v_bfe_u32 v41, v69, 16, 1
	v_add3_u32 v41, v69, v41, s23
	v_lshrrev_b32_e32 v41, 16, v41
	v_and_or_b32 v41, v42, s24, v41
	v_add_lshl_u32 v42, s4, v56, 11
	v_mov_b32_e32 v43, v3
	v_lshl_add_u64 v[42:43], v[44:45], 0, v[42:43]
	global_store_dwordx4 v[42:43], v[38:41], off
	s_waitcnt lgkmcnt(0)

.LBB0_28:
	v_lshl_add_u64 v[40:41], v[36:37], 0, s[4:5]
	v_lshl_add_u64 v[42:43], v[34:35], 0, s[4:5]
	v_lshl_add_u64 v[44:45], v[32:33], 0, s[4:5]
	v_lshl_add_u64 v[46:47], v[30:31], 0, s[4:5]
	v_lshl_add_u64 v[48:49], v[28:29], 0, s[4:5]
	v_lshl_add_u64 v[50:51], v[26:27], 0, s[4:5]
	v_lshl_add_u64 v[52:53], v[24:25], 0, s[4:5]
	v_lshl_add_u64 v[66:67], v[38:39], 0, s[4:5]
	global_load_dword v150, v[40:41], off nt
	global_load_dword v151, v[42:43], off nt
	global_load_dword v152, v[44:45], off nt
	global_load_dword v153, v[46:47], off nt
	global_load_dword v154, v[48:49], off nt
	global_load_dword v155, v[50:51], off nt
	global_load_dword v156, v[52:53], off nt
	global_load_dword v157, v[66:67], off nt
	s_add_u32 s4, s4, 0x10000
	s_addc_u32 s5, s5, 0
	v_lshl_add_u64 v[40:41], v[36:37], 0, s[4:5]
	v_lshl_add_u64 v[42:43], v[34:35], 0, s[4:5]
	v_lshl_add_u64 v[44:45], v[32:33], 0, s[4:5]
	v_lshl_add_u64 v[46:47], v[30:31], 0, s[4:5]
	v_lshl_add_u64 v[48:49], v[28:29], 0, s[4:5]
	v_lshl_add_u64 v[50:51], v[26:27], 0, s[4:5]
	v_lshl_add_u64 v[52:53], v[24:25], 0, s[4:5]
	v_lshl_add_u64 v[66:67], v[38:39], 0, s[4:5]
	global_load_dword v158, v[40:41], off nt
	global_load_dword v159, v[42:43], off nt
	global_load_dword v160, v[44:45], off nt
	global_load_dword v161, v[46:47], off nt
	global_load_dword v162, v[48:49], off nt
	global_load_dword v163, v[50:51], off nt
	global_load_dword v164, v[52:53], off nt
	global_load_dword v165, v[66:67], off nt
	s_add_u32 s4, s4, 0x10000
	s_addc_u32 s5, s5, 0
	v_lshl_add_u64 v[40:41], v[36:37], 0, s[4:5]
	v_lshl_add_u64 v[42:43], v[34:35], 0, s[4:5]
	v_lshl_add_u64 v[44:45], v[32:33], 0, s[4:5]
	v_lshl_add_u64 v[46:47], v[30:31], 0, s[4:5]
	v_lshl_add_u64 v[48:49], v[28:29], 0, s[4:5]
	v_lshl_add_u64 v[50:51], v[26:27], 0, s[4:5]
	v_lshl_add_u64 v[52:53], v[24:25], 0, s[4:5]
	v_lshl_add_u64 v[66:67], v[38:39], 0, s[4:5]
	global_load_dword v166, v[40:41], off nt
	global_load_dword v167, v[42:43], off nt
	global_load_dword v168, v[44:45], off nt
	global_load_dword v169, v[46:47], off nt
	global_load_dword v170, v[48:49], off nt
	global_load_dword v171, v[50:51], off nt
	global_load_dword v172, v[52:53], off nt
	global_load_dword v173, v[66:67], off nt
	s_add_u32 s4, s4, 0x10000
	s_addc_u32 s5, s5, 0
	v_lshl_add_u64 v[40:41], v[36:37], 0, s[4:5]
	v_lshl_add_u64 v[42:43], v[34:35], 0, s[4:5]
	v_lshl_add_u64 v[44:45], v[32:33], 0, s[4:5]
	v_lshl_add_u64 v[46:47], v[30:31], 0, s[4:5]
	v_lshl_add_u64 v[48:49], v[28:29], 0, s[4:5]
	v_lshl_add_u64 v[50:51], v[26:27], 0, s[4:5]
	v_lshl_add_u64 v[52:53], v[24:25], 0, s[4:5]
	v_lshl_add_u64 v[66:67], v[38:39], 0, s[4:5]
	global_load_dword v174, v[40:41], off nt
	global_load_dword v175, v[42:43], off nt
	global_load_dword v176, v[44:45], off nt
	global_load_dword v177, v[46:47], off nt
	global_load_dword v178, v[48:49], off nt
	global_load_dword v179, v[50:51], off nt
	global_load_dword v180, v[52:53], off nt
	global_load_dword v181, v[66:67], off nt
	s_add_u32 s4, s4, 0x10000
	s_addc_u32 s5, s5, 0
	v_add_u32_e32 v48, 0x400, v2
	s_waitcnt vmcnt(30)
	ds_write2_b32 v2, v150, v151 offset1:66
	s_waitcnt vmcnt(28)
	ds_write2_b32 v2, v152, v153 offset0:132 offset1:198
	s_waitcnt vmcnt(26)
	ds_write2_b32 v48, v154, v155 offset0:8 offset1:74
	s_waitcnt vmcnt(24)
	ds_write2_b32 v48, v156, v157 offset0:140 offset1:206
	v_add_u32_e32 v2, 0x840, v2
	v_add_u32_e32 v48, 0x400, v2
	s_waitcnt vmcnt(22)
	ds_write2_b32 v2, v158, v159 offset1:66
	s_waitcnt vmcnt(20)
	ds_write2_b32 v2, v160, v161 offset0:132 offset1:198
	s_waitcnt vmcnt(18)
	ds_write2_b32 v48, v162, v163 offset0:8 offset1:74
	s_waitcnt vmcnt(16)
	ds_write2_b32 v48, v164, v165 offset0:140 offset1:206
	v_add_u32_e32 v2, 0x840, v2
	v_add_u32_e32 v48, 0x400, v2
	s_waitcnt vmcnt(14)
	ds_write2_b32 v2, v166, v167 offset1:66
	s_waitcnt vmcnt(12)
	ds_write2_b32 v2, v168, v169 offset0:132 offset1:198
	s_waitcnt vmcnt(10)
	ds_write2_b32 v48, v170, v171 offset0:8 offset1:74
	s_waitcnt vmcnt(8)
	ds_write2_b32 v48, v172, v173 offset0:140 offset1:206
	v_add_u32_e32 v2, 0x840, v2
	v_add_u32_e32 v48, 0x400, v2
	s_waitcnt vmcnt(6)
	ds_write2_b32 v2, v174, v175 offset1:66
	s_waitcnt vmcnt(4)
	ds_write2_b32 v2, v176, v177 offset0:132 offset1:198
	s_waitcnt vmcnt(2)
	ds_write2_b32 v48, v178, v179 offset0:8 offset1:74
	s_waitcnt vmcnt(0)
	ds_write2_b32 v48, v180, v181 offset0:140 offset1:206
	v_add_u32_e32 v2, 0x840, v2
	s_cmp_lg_u32 s4, 0x40000
	s_waitcnt lgkmcnt(0)
	ds_read2_b32 v[28:29], v17 offset1:8
	ds_read2_b32 v[32:33], v17 offset0:33 offset1:41
	ds_read2_b32 v[34:35], v17 offset0:66 offset1:74
	ds_read2_b32 v[36:37], v17 offset0:99 offset1:107
	ds_read2_b32 v[38:39], v17 offset0:132 offset1:140
	s_waitcnt lgkmcnt(4)
	v_bfe_u32 v2, v28, 16, 1
	v_add3_u32 v2, v28, v2, s23
	s_waitcnt lgkmcnt(3)
	v_bfe_u32 v24, v32, 16, 1
	v_lshrrev_b32_e32 v2, 16, v2
	v_add3_u32 v24, v32, v24, s23
	ds_read2_b32 v[40:41], v17 offset0:165 offset1:173
	v_and_or_b32 v24, v24, s24, v2
	s_waitcnt lgkmcnt(3)
	v_bfe_u32 v2, v34, 16, 1
	v_add3_u32 v2, v34, v2, s23
	s_waitcnt lgkmcnt(2)
	v_bfe_u32 v25, v36, 16, 1
	ds_read2_b32 v[42:43], v17 offset0:198 offset1:206
	v_lshrrev_b32_e32 v2, 16, v2
	v_add3_u32 v25, v36, v25, s23
	ds_read2_b32 v[44:45], v17 offset0:231 offset1:239
	v_and_or_b32 v25, v25, s24, v2
	s_waitcnt lgkmcnt(3)
	v_bfe_u32 v2, v38, 16, 1
	v_add3_u32 v2, v38, v2, s23
	s_waitcnt lgkmcnt(2)
	v_bfe_u32 v26, v40, 16, 1
	v_lshrrev_b32_e32 v2, 16, v2
	v_add3_u32 v26, v40, v26, s23
	v_and_or_b32 v26, v26, s24, v2
	s_waitcnt lgkmcnt(1)
	v_bfe_u32 v2, v42, 16, 1
	s_lshl_b32 s0, s25, 5
	v_add3_u32 v2, v42, v2, s23
	s_waitcnt lgkmcnt(0)
	v_bfe_u32 v27, v44, 16, 1
	s_and_b32 s4, s0, 0x3e0
	s_lshl_b32 s0, s25, 2
	v_lshrrev_b32_e32 v2, 16, v2
	v_add3_u32 v27, v44, v27, s23
	s_and_b32 s0, s0, 0x380
	v_and_or_b32 v27, v27, s24, v2
	v_or_b32_e32 v2, s4, v1
	v_lshl_add_u64 v[30:31], v[8:9], 0, s[0:1]
	v_lshlrev_b32_e32 v2, 11, v2
	v_lshl_add_u64 v[46:47], v[30:31], 0, v[2:3]
	v_bfe_u32 v2, v29, 16, 1
	global_store_dwordx4 v[46:47], v[24:27], off
	v_add3_u32 v2, v29, v2, s23
	v_lshrrev_b32_e32 v2, 16, v2
	v_bfe_u32 v24, v33, 16, 1
	v_add3_u32 v24, v33, v24, s23
	v_and_or_b32 v24, v24, s24, v2
	v_bfe_u32 v2, v35, 16, 1
	v_add3_u32 v2, v35, v2, s23
	v_bfe_u32 v25, v37, 16, 1
	v_lshrrev_b32_e32 v2, 16, v2
	v_add3_u32 v25, v37, v25, s23
	v_and_or_b32 v25, v25, s24, v2
	v_bfe_u32 v2, v39, 16, 1
	v_add3_u32 v2, v39, v2, s23
	v_bfe_u32 v26, v41, 16, 1
	v_lshrrev_b32_e32 v2, 16, v2
	v_add3_u32 v26, v41, v26, s23
	v_and_or_b32 v26, v26, s24, v2
	v_bfe_u32 v2, v43, 16, 1
	v_add3_u32 v2, v43, v2, s23
	v_bfe_u32 v27, v45, 16, 1
	v_lshrrev_b32_e32 v2, 16, v2
	v_add3_u32 v27, v45, v27, s23
	v_and_or_b32 v27, v27, s24, v2
	v_or_b32_e32 v2, s4, v54
	v_lshlrev_b32_e32 v2, 11, v2
	ds_read2_b32 v[28:29], v17 offset0:16 offset1:24
	v_lshl_add_u64 v[32:33], v[30:31], 0, v[2:3]
	global_store_dwordx4 v[32:33], v[24:27], off
	ds_read2_b32 v[32:33], v17 offset0:49 offset1:57
	ds_read2_b32 v[34:35], v17 offset0:82 offset1:90
	ds_read2_b32 v[36:37], v17 offset0:115 offset1:123
	s_waitcnt lgkmcnt(3)
	v_bfe_u32 v2, v28, 16, 1
	v_add3_u32 v2, v28, v2, s23
	s_waitcnt lgkmcnt(2)
	v_bfe_u32 v24, v32, 16, 1
	ds_read2_b32 v[38:39], v17 offset0:148 offset1:156
	v_lshrrev_b32_e32 v2, 16, v2
	v_add3_u32 v24, v32, v24, s23
	ds_read2_b32 v[40:41], v17 offset0:181 offset1:189
	v_and_or_b32 v24, v24, s24, v2
	s_waitcnt lgkmcnt(3)
	v_bfe_u32 v2, v34, 16, 1
	v_add3_u32 v2, v34, v2, s23
	s_waitcnt lgkmcnt(2)
	v_bfe_u32 v25, v36, 16, 1
	ds_read2_b32 v[42:43], v17 offset0:214 offset1:222
	v_lshrrev_b32_e32 v2, 16, v2
	v_add3_u32 v25, v36, v25, s23
	ds_read2_b32 v[44:45], v17 offset0:247 offset1:255
	v_and_or_b32 v25, v25, s24, v2
	s_waitcnt lgkmcnt(3)
	v_bfe_u32 v2, v38, 16, 1
	v_add3_u32 v2, v38, v2, s23
	s_waitcnt lgkmcnt(2)
	v_bfe_u32 v26, v40, 16, 1
	v_lshrrev_b32_e32 v2, 16, v2
	v_add3_u32 v26, v40, v26, s23
	v_and_or_b32 v26, v26, s24, v2
	s_waitcnt lgkmcnt(1)
	v_bfe_u32 v2, v42, 16, 1
	v_add3_u32 v2, v42, v2, s23
	s_waitcnt lgkmcnt(0)
	v_bfe_u32 v27, v44, 16, 1
	v_lshrrev_b32_e32 v2, 16, v2
	v_add3_u32 v27, v44, v27, s23
	v_and_or_b32 v27, v27, s24, v2
	v_or_b32_e32 v2, s4, v55
	v_lshlrev_b32_e32 v2, 11, v2
	v_lshl_add_u64 v[46:47], v[30:31], 0, v[2:3]
	v_bfe_u32 v2, v29, 16, 1
	global_store_dwordx4 v[46:47], v[24:27], off
	v_add3_u32 v2, v29, v2, s23
	v_lshrrev_b32_e32 v2, 16, v2
	v_bfe_u32 v24, v33, 16, 1
	v_add3_u32 v24, v33, v24, s23
	v_and_or_b32 v24, v24, s24, v2
	v_bfe_u32 v2, v35, 16, 1
	v_add3_u32 v2, v35, v2, s23
	v_bfe_u32 v25, v37, 16, 1
	v_lshrrev_b32_e32 v2, 16, v2
	v_add3_u32 v25, v37, v25, s23
	v_and_or_b32 v25, v25, s24, v2
	v_bfe_u32 v2, v39, 16, 1
	v_add3_u32 v2, v39, v2, s23
	v_bfe_u32 v26, v41, 16, 1
	v_lshrrev_b32_e32 v2, 16, v2
	v_add3_u32 v26, v41, v26, s23
	v_and_or_b32 v26, v26, s24, v2
	v_bfe_u32 v2, v43, 16, 1
	v_add3_u32 v2, v43, v2, s23
	v_bfe_u32 v27, v45, 16, 1
	v_lshrrev_b32_e32 v2, 16, v2
	v_add3_u32 v27, v45, v27, s23
	v_and_or_b32 v27, v27, s24, v2
	v_add_lshl_u32 v2, s4, v56, 11
	v_lshl_add_u64 v[28:29], v[30:31], 0, v[2:3]
	global_store_dwordx4 v[28:29], v[24:27], off
	s_waitcnt lgkmcnt(0)

.LBB0_33:
	v_lshl_add_u64 v[40:41], v[38:39], 0, s[4:5]
	v_lshl_add_u64 v[42:43], v[36:37], 0, s[4:5]
	v_lshl_add_u64 v[44:45], v[34:35], 0, s[4:5]
	v_lshl_add_u64 v[46:47], v[32:33], 0, s[4:5]
	v_lshl_add_u64 v[48:49], v[30:31], 0, s[4:5]
	v_lshl_add_u64 v[50:51], v[28:29], 0, s[4:5]
	v_lshl_add_u64 v[52:53], v[26:27], 0, s[4:5]
	v_lshl_add_u64 v[66:67], v[24:25], 0, s[4:5]
	global_load_dword v150, v[40:41], off nt
	global_load_dword v151, v[42:43], off nt
	global_load_dword v152, v[44:45], off nt
	global_load_dword v153, v[46:47], off nt
	global_load_dword v154, v[48:49], off nt
	global_load_dword v155, v[50:51], off nt
	global_load_dword v156, v[52:53], off nt
	global_load_dword v157, v[66:67], off nt
	s_add_u32 s4, s4, 0x20000
	s_addc_u32 s5, s5, 0
	v_lshl_add_u64 v[40:41], v[38:39], 0, s[4:5]
	v_lshl_add_u64 v[42:43], v[36:37], 0, s[4:5]
	v_lshl_add_u64 v[44:45], v[34:35], 0, s[4:5]
	v_lshl_add_u64 v[46:47], v[32:33], 0, s[4:5]
	v_lshl_add_u64 v[48:49], v[30:31], 0, s[4:5]
	v_lshl_add_u64 v[50:51], v[28:29], 0, s[4:5]
	v_lshl_add_u64 v[52:53], v[26:27], 0, s[4:5]
	v_lshl_add_u64 v[66:67], v[24:25], 0, s[4:5]
	global_load_dword v158, v[40:41], off nt
	global_load_dword v159, v[42:43], off nt
	global_load_dword v160, v[44:45], off nt
	global_load_dword v161, v[46:47], off nt
	global_load_dword v162, v[48:49], off nt
	global_load_dword v163, v[50:51], off nt
	global_load_dword v164, v[52:53], off nt
	global_load_dword v165, v[66:67], off nt
	s_add_u32 s4, s4, 0x20000
	s_addc_u32 s5, s5, 0
	v_lshl_add_u64 v[40:41], v[38:39], 0, s[4:5]
	v_lshl_add_u64 v[42:43], v[36:37], 0, s[4:5]
	v_lshl_add_u64 v[44:45], v[34:35], 0, s[4:5]
	v_lshl_add_u64 v[46:47], v[32:33], 0, s[4:5]
	v_lshl_add_u64 v[48:49], v[30:31], 0, s[4:5]
	v_lshl_add_u64 v[50:51], v[28:29], 0, s[4:5]
	v_lshl_add_u64 v[52:53], v[26:27], 0, s[4:5]
	v_lshl_add_u64 v[66:67], v[24:25], 0, s[4:5]
	global_load_dword v166, v[40:41], off nt
	global_load_dword v167, v[42:43], off nt
	global_load_dword v168, v[44:45], off nt
	global_load_dword v169, v[46:47], off nt
	global_load_dword v170, v[48:49], off nt
	global_load_dword v171, v[50:51], off nt
	global_load_dword v172, v[52:53], off nt
	global_load_dword v173, v[66:67], off nt
	s_add_u32 s4, s4, 0x20000
	s_addc_u32 s5, s5, 0
	v_lshl_add_u64 v[40:41], v[38:39], 0, s[4:5]
	v_lshl_add_u64 v[42:43], v[36:37], 0, s[4:5]
	v_lshl_add_u64 v[44:45], v[34:35], 0, s[4:5]
	v_lshl_add_u64 v[46:47], v[32:33], 0, s[4:5]
	v_lshl_add_u64 v[48:49], v[30:31], 0, s[4:5]
	v_lshl_add_u64 v[50:51], v[28:29], 0, s[4:5]
	v_lshl_add_u64 v[52:53], v[26:27], 0, s[4:5]
	v_lshl_add_u64 v[66:67], v[24:25], 0, s[4:5]
	global_load_dword v174, v[40:41], off nt
	global_load_dword v175, v[42:43], off nt
	global_load_dword v176, v[44:45], off nt
	global_load_dword v177, v[46:47], off nt
	global_load_dword v178, v[48:49], off nt
	global_load_dword v179, v[50:51], off nt
	global_load_dword v180, v[52:53], off nt
	global_load_dword v181, v[66:67], off nt
	s_add_u32 s4, s4, 0x20000
	s_addc_u32 s5, s5, 0
	v_add_u32_e32 v48, 0x400, v2
	s_waitcnt vmcnt(30)
	ds_write2_b32 v2, v150, v151 offset1:66
	s_waitcnt vmcnt(28)
	ds_write2_b32 v2, v152, v153 offset0:132 offset1:198
	s_waitcnt vmcnt(26)
	ds_write2_b32 v48, v154, v155 offset0:8 offset1:74
	s_waitcnt vmcnt(24)
	ds_write2_b32 v48, v156, v157 offset0:140 offset1:206
	v_add_u32_e32 v2, 0x840, v2
	v_add_u32_e32 v48, 0x400, v2
	s_waitcnt vmcnt(22)
	ds_write2_b32 v2, v158, v159 offset1:66
	s_waitcnt vmcnt(20)
	ds_write2_b32 v2, v160, v161 offset0:132 offset1:198
	s_waitcnt vmcnt(18)
	ds_write2_b32 v48, v162, v163 offset0:8 offset1:74
	s_waitcnt vmcnt(16)
	ds_write2_b32 v48, v164, v165 offset0:140 offset1:206
	v_add_u32_e32 v2, 0x840, v2
	v_add_u32_e32 v48, 0x400, v2
	s_waitcnt vmcnt(14)
	ds_write2_b32 v2, v166, v167 offset1:66
	s_waitcnt vmcnt(12)
	ds_write2_b32 v2, v168, v169 offset0:132 offset1:198
	s_waitcnt vmcnt(10)
	ds_write2_b32 v48, v170, v171 offset0:8 offset1:74
	s_waitcnt vmcnt(8)
	ds_write2_b32 v48, v172, v173 offset0:140 offset1:206
	v_add_u32_e32 v2, 0x840, v2
	v_add_u32_e32 v48, 0x400, v2
	s_waitcnt vmcnt(6)
	ds_write2_b32 v2, v174, v175 offset1:66
	s_waitcnt vmcnt(4)
	ds_write2_b32 v2, v176, v177 offset0:132 offset1:198
	s_waitcnt vmcnt(2)
	ds_write2_b32 v48, v178, v179 offset0:8 offset1:74
	s_waitcnt vmcnt(0)
	ds_write2_b32 v48, v180, v181 offset0:140 offset1:206
	v_add_u32_e32 v2, 0x840, v2
	s_cmp_lg_u32 s4, 0x80000
	s_waitcnt lgkmcnt(0)
	ds_read2_b32 v[28:29], v17 offset1:8
	ds_read2_b32 v[32:33], v17 offset0:33 offset1:41
	ds_read2_b32 v[34:35], v17 offset0:66 offset1:74
	ds_read2_b32 v[36:37], v17 offset0:99 offset1:107
	ds_read2_b32 v[38:39], v17 offset0:132 offset1:140
	s_waitcnt lgkmcnt(4)
	v_bfe_u32 v2, v28, 16, 1
	v_add3_u32 v2, v28, v2, s23
	s_waitcnt lgkmcnt(3)
	v_bfe_u32 v24, v32, 16, 1
	v_lshrrev_b32_e32 v2, 16, v2
	v_add3_u32 v24, v32, v24, s23
	ds_read2_b32 v[40:41], v17 offset0:165 offset1:173
	v_and_or_b32 v24, v24, s24, v2
	s_waitcnt lgkmcnt(3)
	v_bfe_u32 v2, v34, 16, 1
	v_add3_u32 v2, v34, v2, s23
	s_waitcnt lgkmcnt(2)
	v_bfe_u32 v25, v36, 16, 1
	ds_read2_b32 v[42:43], v17 offset0:198 offset1:206
	v_lshrrev_b32_e32 v2, 16, v2
	v_add3_u32 v25, v36, v25, s23
	ds_read2_b32 v[44:45], v17 offset0:231 offset1:239
	v_and_or_b32 v25, v25, s24, v2
	s_waitcnt lgkmcnt(3)
	v_bfe_u32 v2, v38, 16, 1
	v_add3_u32 v2, v38, v2, s23
	s_waitcnt lgkmcnt(2)
	v_bfe_u32 v26, v40, 16, 1
	v_lshrrev_b32_e32 v2, 16, v2
	v_add3_u32 v26, v40, v26, s23
	s_lshl_b32 s4, s25, 5
	v_and_or_b32 v26, v26, s24, v2
	s_waitcnt lgkmcnt(1)
	v_bfe_u32 v2, v42, 16, 1
	s_add_i32 s0, s25, 0xf800
	s_and_b32 s4, s4, 0x7e0
	v_add3_u32 v2, v42, v2, s23
	s_waitcnt lgkmcnt(0)
	v_bfe_u32 v27, v44, 16, 1
	s_and_b32 s0, s0, 0xffc0
	s_bitset1_b32 s4, 12
	v_lshrrev_b32_e32 v2, 16, v2
	v_add3_u32 v27, v44, v27, s23
	s_lshl_b32 s0, s0, 1
	v_and_or_b32 v27, v27, s24, v2
	v_or_b32_e32 v2, s4, v1
	v_lshl_add_u64 v[30:31], v[10:11], 0, s[0:1]
	v_lshlrev_b32_e32 v2, 11, v2
	v_lshl_add_u64 v[46:47], v[30:31], 0, v[2:3]
	v_bfe_u32 v2, v29, 16, 1
	global_store_dwordx4 v[46:47], v[24:27], off
	v_add3_u32 v2, v29, v2, s23
	v_lshrrev_b32_e32 v2, 16, v2
	v_bfe_u32 v24, v33, 16, 1
	v_add3_u32 v24, v33, v24, s23
	v_and_or_b32 v24, v24, s24, v2
	v_bfe_u32 v2, v35, 16, 1
	v_add3_u32 v2, v35, v2, s23
	v_bfe_u32 v25, v37, 16, 1
	v_lshrrev_b32_e32 v2, 16, v2
	v_add3_u32 v25, v37, v25, s23
	v_and_or_b32 v25, v25, s24, v2
	v_bfe_u32 v2, v39, 16, 1
	v_add3_u32 v2, v39, v2, s23
	v_bfe_u32 v26, v41, 16, 1
	v_lshrrev_b32_e32 v2, 16, v2
	v_add3_u32 v26, v41, v26, s23
	v_and_or_b32 v26, v26, s24, v2
	v_bfe_u32 v2, v43, 16, 1
	v_add3_u32 v2, v43, v2, s23
	v_bfe_u32 v27, v45, 16, 1
	v_lshrrev_b32_e32 v2, 16, v2
	v_add3_u32 v27, v45, v27, s23
	v_and_or_b32 v27, v27, s24, v2
	v_or_b32_e32 v2, s4, v54
	v_lshlrev_b32_e32 v2, 11, v2
	ds_read2_b32 v[28:29], v17 offset0:16 offset1:24
	v_lshl_add_u64 v[32:33], v[30:31], 0, v[2:3]
	global_store_dwordx4 v[32:33], v[24:27], off
	ds_read2_b32 v[32:33], v17 offset0:49 offset1:57
	ds_read2_b32 v[34:35], v17 offset0:82 offset1:90
	ds_read2_b32 v[36:37], v17 offset0:115 offset1:123
	s_waitcnt lgkmcnt(3)
	v_bfe_u32 v2, v28, 16, 1
	v_add3_u32 v2, v28, v2, s23
	s_waitcnt lgkmcnt(2)
	v_bfe_u32 v24, v32, 16, 1
	ds_read2_b32 v[38:39], v17 offset0:148 offset1:156
	v_lshrrev_b32_e32 v2, 16, v2
	v_add3_u32 v24, v32, v24, s23
	ds_read2_b32 v[40:41], v17 offset0:181 offset1:189
	v_and_or_b32 v24, v24, s24, v2
	s_waitcnt lgkmcnt(3)
	v_bfe_u32 v2, v34, 16, 1
	v_add3_u32 v2, v34, v2, s23
	s_waitcnt lgkmcnt(2)
	v_bfe_u32 v25, v36, 16, 1
	ds_read2_b32 v[42:43], v17 offset0:214 offset1:222
	v_lshrrev_b32_e32 v2, 16, v2
	v_add3_u32 v25, v36, v25, s23
	ds_read2_b32 v[44:45], v17 offset0:247 offset1:255
	v_and_or_b32 v25, v25, s24, v2
	s_waitcnt lgkmcnt(3)
	v_bfe_u32 v2, v38, 16, 1
	v_add3_u32 v2, v38, v2, s23
	s_waitcnt lgkmcnt(2)
	v_bfe_u32 v26, v40, 16, 1
	v_lshrrev_b32_e32 v2, 16, v2
	v_add3_u32 v26, v40, v26, s23
	v_and_or_b32 v26, v26, s24, v2
	s_waitcnt lgkmcnt(1)
	v_bfe_u32 v2, v42, 16, 1
	v_add3_u32 v2, v42, v2, s23
	s_waitcnt lgkmcnt(0)
	v_bfe_u32 v27, v44, 16, 1
	v_lshrrev_b32_e32 v2, 16, v2
	v_add3_u32 v27, v44, v27, s23
	v_and_or_b32 v27, v27, s24, v2
	v_or_b32_e32 v2, s4, v55
	v_lshlrev_b32_e32 v2, 11, v2
	v_lshl_add_u64 v[46:47], v[30:31], 0, v[2:3]
	v_bfe_u32 v2, v29, 16, 1
	global_store_dwordx4 v[46:47], v[24:27], off
	v_add3_u32 v2, v29, v2, s23
	v_lshrrev_b32_e32 v2, 16, v2
	v_bfe_u32 v24, v33, 16, 1
	v_add3_u32 v24, v33, v24, s23
	v_and_or_b32 v24, v24, s24, v2
	v_bfe_u32 v2, v35, 16, 1
	v_add3_u32 v2, v35, v2, s23
	v_bfe_u32 v25, v37, 16, 1
	v_lshrrev_b32_e32 v2, 16, v2
	v_add3_u32 v25, v37, v25, s23
	v_and_or_b32 v25, v25, s24, v2
	v_bfe_u32 v2, v39, 16, 1
	v_add3_u32 v2, v39, v2, s23
	v_bfe_u32 v26, v41, 16, 1
	v_lshrrev_b32_e32 v2, 16, v2
	v_add3_u32 v26, v41, v26, s23
	v_and_or_b32 v26, v26, s24, v2
	v_bfe_u32 v2, v43, 16, 1
	v_add3_u32 v2, v43, v2, s23
	v_bfe_u32 v27, v45, 16, 1
	v_lshrrev_b32_e32 v2, 16, v2
	v_add3_u32 v27, v45, v27, s23
	v_and_or_b32 v27, v27, s24, v2
	v_add_lshl_u32 v2, s4, v56, 11
	v_lshl_add_u64 v[28:29], v[30:31], 0, v[2:3]
	global_store_dwordx4 v[28:29], v[24:27], off
	s_waitcnt lgkmcnt(0)

.LBB0_38:
	v_lshl_add_u64 v[40:41], v[38:39], 0, s[16:17]
	v_lshl_add_u64 v[42:43], v[36:37], 0, s[16:17]
	v_lshl_add_u64 v[44:45], v[34:35], 0, s[16:17]
	v_lshl_add_u64 v[46:47], v[32:33], 0, s[16:17]
	v_lshl_add_u64 v[48:49], v[30:31], 0, s[16:17]
	v_lshl_add_u64 v[50:51], v[28:29], 0, s[16:17]
	v_lshl_add_u64 v[52:53], v[26:27], 0, s[16:17]
	v_lshl_add_u64 v[66:67], v[24:25], 0, s[16:17]
	global_load_dword v150, v[40:41], off nt
	global_load_dword v151, v[42:43], off nt
	global_load_dword v152, v[44:45], off nt
	global_load_dword v153, v[46:47], off nt
	global_load_dword v154, v[48:49], off nt
	global_load_dword v155, v[50:51], off nt
	global_load_dword v156, v[52:53], off nt
	global_load_dword v157, v[66:67], off nt
	s_add_u32 s16, s16, 0x40000
	s_addc_u32 s17, s17, 0
	v_lshl_add_u64 v[40:41], v[38:39], 0, s[16:17]
	v_lshl_add_u64 v[42:43], v[36:37], 0, s[16:17]
	v_lshl_add_u64 v[44:45], v[34:35], 0, s[16:17]
	v_lshl_add_u64 v[46:47], v[32:33], 0, s[16:17]
	v_lshl_add_u64 v[48:49], v[30:31], 0, s[16:17]
	v_lshl_add_u64 v[50:51], v[28:29], 0, s[16:17]
	v_lshl_add_u64 v[52:53], v[26:27], 0, s[16:17]
	v_lshl_add_u64 v[66:67], v[24:25], 0, s[16:17]
	global_load_dword v158, v[40:41], off nt
	global_load_dword v159, v[42:43], off nt
	global_load_dword v160, v[44:45], off nt
	global_load_dword v161, v[46:47], off nt
	global_load_dword v162, v[48:49], off nt
	global_load_dword v163, v[50:51], off nt
	global_load_dword v164, v[52:53], off nt
	global_load_dword v165, v[66:67], off nt
	s_add_u32 s16, s16, 0x40000
	s_addc_u32 s17, s17, 0
	v_lshl_add_u64 v[40:41], v[38:39], 0, s[16:17]
	v_lshl_add_u64 v[42:43], v[36:37], 0, s[16:17]
	v_lshl_add_u64 v[44:45], v[34:35], 0, s[16:17]
	v_lshl_add_u64 v[46:47], v[32:33], 0, s[16:17]
	v_lshl_add_u64 v[48:49], v[30:31], 0, s[16:17]
	v_lshl_add_u64 v[50:51], v[28:29], 0, s[16:17]
	v_lshl_add_u64 v[52:53], v[26:27], 0, s[16:17]
	v_lshl_add_u64 v[66:67], v[24:25], 0, s[16:17]
	global_load_dword v166, v[40:41], off nt
	global_load_dword v167, v[42:43], off nt
	global_load_dword v168, v[44:45], off nt
	global_load_dword v169, v[46:47], off nt
	global_load_dword v170, v[48:49], off nt
	global_load_dword v171, v[50:51], off nt
	global_load_dword v172, v[52:53], off nt
	global_load_dword v173, v[66:67], off nt
	s_add_u32 s16, s16, 0x40000
	s_addc_u32 s17, s17, 0
	v_lshl_add_u64 v[40:41], v[38:39], 0, s[16:17]
	v_lshl_add_u64 v[42:43], v[36:37], 0, s[16:17]
	v_lshl_add_u64 v[44:45], v[34:35], 0, s[16:17]
	v_lshl_add_u64 v[46:47], v[32:33], 0, s[16:17]
	v_lshl_add_u64 v[48:49], v[30:31], 0, s[16:17]
	v_lshl_add_u64 v[50:51], v[28:29], 0, s[16:17]
	v_lshl_add_u64 v[52:53], v[26:27], 0, s[16:17]
	v_lshl_add_u64 v[66:67], v[24:25], 0, s[16:17]
	global_load_dword v174, v[40:41], off nt
	global_load_dword v175, v[42:43], off nt
	global_load_dword v176, v[44:45], off nt
	global_load_dword v177, v[46:47], off nt
	global_load_dword v178, v[48:49], off nt
	global_load_dword v179, v[50:51], off nt
	global_load_dword v180, v[52:53], off nt
	global_load_dword v181, v[66:67], off nt
	s_add_u32 s16, s16, 0x40000
	s_addc_u32 s17, s17, 0
	v_add_u32_e32 v48, 0x400, v2
	s_waitcnt vmcnt(30)
	ds_write2_b32 v2, v150, v151 offset1:66
	s_waitcnt vmcnt(28)
	ds_write2_b32 v2, v152, v153 offset0:132 offset1:198
	s_waitcnt vmcnt(26)
	ds_write2_b32 v48, v154, v155 offset0:8 offset1:74
	s_waitcnt vmcnt(24)
	ds_write2_b32 v48, v156, v157 offset0:140 offset1:206
	v_add_u32_e32 v2, 0x840, v2
	v_add_u32_e32 v48, 0x400, v2
	s_waitcnt vmcnt(22)
	ds_write2_b32 v2, v158, v159 offset1:66
	s_waitcnt vmcnt(20)
	ds_write2_b32 v2, v160, v161 offset0:132 offset1:198
	s_waitcnt vmcnt(18)
	ds_write2_b32 v48, v162, v163 offset0:8 offset1:74
	s_waitcnt vmcnt(16)
	ds_write2_b32 v48, v164, v165 offset0:140 offset1:206
	v_add_u32_e32 v2, 0x840, v2
	v_add_u32_e32 v48, 0x400, v2
	s_waitcnt vmcnt(14)
	ds_write2_b32 v2, v166, v167 offset1:66
	s_waitcnt vmcnt(12)
	ds_write2_b32 v2, v168, v169 offset0:132 offset1:198
	s_waitcnt vmcnt(10)
	ds_write2_b32 v48, v170, v171 offset0:8 offset1:74
	s_waitcnt vmcnt(8)
	ds_write2_b32 v48, v172, v173 offset0:140 offset1:206
	v_add_u32_e32 v2, 0x840, v2
	v_add_u32_e32 v48, 0x400, v2
	s_waitcnt vmcnt(6)
	ds_write2_b32 v2, v174, v175 offset1:66
	s_waitcnt vmcnt(4)
	ds_write2_b32 v2, v176, v177 offset0:132 offset1:198
	s_waitcnt vmcnt(2)
	ds_write2_b32 v48, v178, v179 offset0:8 offset1:74
	s_waitcnt vmcnt(0)
	ds_write2_b32 v48, v180, v181 offset0:140 offset1:206
	v_add_u32_e32 v2, 0x840, v2
	s_cmp_lg_u32 s16, 0x100000
	s_waitcnt lgkmcnt(0)
	ds_read2_b32 v[28:29], v17 offset1:8
	ds_read2_b32 v[30:31], v17 offset0:33 offset1:41
	ds_read2_b32 v[34:35], v17 offset0:66 offset1:74
	ds_read2_b32 v[36:37], v17 offset0:99 offset1:107
	ds_read2_b32 v[38:39], v17 offset0:132 offset1:140
	s_waitcnt lgkmcnt(4)
	v_bfe_u32 v2, v28, 16, 1
	s_waitcnt lgkmcnt(3)
	v_bfe_u32 v24, v30, 16, 1
	v_add3_u32 v2, v28, v2, s23
	v_lshrrev_b32_e32 v2, 16, v2
	v_add3_u32 v24, v30, v24, s23
	ds_read2_b32 v[40:41], v17 offset0:165 offset1:173
	v_and_or_b32 v24, v24, s24, v2
	s_waitcnt lgkmcnt(3)
	v_bfe_u32 v2, v34, 16, 1
	v_add3_u32 v2, v34, v2, s23
	s_waitcnt lgkmcnt(2)
	v_bfe_u32 v25, v36, 16, 1
	ds_read2_b32 v[42:43], v17 offset0:198 offset1:206
	v_lshrrev_b32_e32 v2, 16, v2
	v_add3_u32 v25, v36, v25, s23
	ds_read2_b32 v[44:45], v17 offset0:231 offset1:239
	v_and_or_b32 v25, v25, s24, v2
	s_waitcnt lgkmcnt(3)
	v_bfe_u32 v2, v38, 16, 1
	v_add3_u32 v2, v38, v2, s23
	s_waitcnt lgkmcnt(2)
	v_bfe_u32 v26, v40, 16, 1
	v_lshrrev_b32_e32 v2, 16, v2
	v_add3_u32 v26, v40, v26, s23
	v_and_or_b32 v26, v26, s24, v2
	s_waitcnt lgkmcnt(1)
	v_bfe_u32 v2, v42, 16, 1
	v_add_u32_e32 v46, s4, v1
	v_add3_u32 v2, v42, v2, s23
	s_waitcnt lgkmcnt(0)
	v_bfe_u32 v27, v44, 16, 1
	v_ashrrev_i32_e32 v47, 31, v46
	v_lshl_add_u64 v[32:33], s[8:9], 1, v[10:11]
	v_lshrrev_b32_e32 v2, 16, v2
	v_add3_u32 v27, v44, v27, s23
	v_lshlrev_b64 v[46:47], 11, v[46:47]
	v_and_or_b32 v27, v27, s24, v2
	v_lshl_add_u64 v[46:47], v[32:33], 0, v[46:47]
	v_bfe_u32 v2, v29, 16, 1
	global_store_dwordx4 v[46:47], v[24:27], off
	v_add3_u32 v2, v29, v2, s23
	v_lshrrev_b32_e32 v2, 16, v2
	v_bfe_u32 v24, v31, 16, 1
	v_add3_u32 v24, v31, v24, s23
	v_and_or_b32 v24, v24, s24, v2
	v_bfe_u32 v2, v35, 16, 1
	v_add3_u32 v2, v35, v2, s23
	v_bfe_u32 v25, v37, 16, 1
	v_lshrrev_b32_e32 v2, 16, v2
	v_add3_u32 v25, v37, v25, s23
	v_and_or_b32 v25, v25, s24, v2
	v_bfe_u32 v2, v39, 16, 1
	v_add3_u32 v2, v39, v2, s23
	v_bfe_u32 v26, v41, 16, 1
	v_lshrrev_b32_e32 v2, 16, v2
	v_add3_u32 v26, v41, v26, s23
	v_and_or_b32 v26, v26, s24, v2
	v_bfe_u32 v2, v43, 16, 1
	v_add_u32_e32 v28, s4, v54
	v_add3_u32 v2, v43, v2, s23
	v_bfe_u32 v27, v45, 16, 1
	v_ashrrev_i32_e32 v29, 31, v28
	v_lshrrev_b32_e32 v2, 16, v2
	v_add3_u32 v27, v45, v27, s23
	v_lshlrev_b64 v[28:29], 11, v[28:29]
	v_and_or_b32 v27, v27, s24, v2
	ds_read2_b32 v[30:31], v17 offset0:16 offset1:24
	v_lshl_add_u64 v[28:29], v[32:33], 0, v[28:29]
	global_store_dwordx4 v[28:29], v[24:27], off
	ds_read2_b32 v[28:29], v17 offset0:49 offset1:57
	ds_read2_b32 v[34:35], v17 offset0:82 offset1:90
	ds_read2_b32 v[36:37], v17 offset0:115 offset1:123
	s_waitcnt lgkmcnt(3)
	v_bfe_u32 v2, v30, 16, 1
	v_add3_u32 v2, v30, v2, s23
	s_waitcnt lgkmcnt(2)
	v_bfe_u32 v24, v28, 16, 1
	ds_read2_b32 v[38:39], v17 offset0:148 offset1:156
	v_lshrrev_b32_e32 v2, 16, v2
	v_add3_u32 v24, v28, v24, s23
	ds_read2_b32 v[40:41], v17 offset0:181 offset1:189
	v_and_or_b32 v24, v24, s24, v2
	s_waitcnt lgkmcnt(3)
	v_bfe_u32 v2, v34, 16, 1
	v_add3_u32 v2, v34, v2, s23
	s_waitcnt lgkmcnt(2)
	v_bfe_u32 v25, v36, 16, 1
	ds_read2_b32 v[42:43], v17 offset0:214 offset1:222
	v_lshrrev_b32_e32 v2, 16, v2
	v_add3_u32 v25, v36, v25, s23
	ds_read2_b32 v[44:45], v17 offset0:247 offset1:255
	v_and_or_b32 v25, v25, s24, v2
	s_waitcnt lgkmcnt(3)
	v_bfe_u32 v2, v38, 16, 1
	v_add3_u32 v2, v38, v2, s23
	s_waitcnt lgkmcnt(2)
	v_bfe_u32 v26, v40, 16, 1
	v_lshrrev_b32_e32 v2, 16, v2
	v_add3_u32 v26, v40, v26, s23
	v_and_or_b32 v26, v26, s24, v2
	s_waitcnt lgkmcnt(1)
	v_bfe_u32 v2, v42, 16, 1
	v_add_u32_e32 v46, s4, v55
	v_add3_u32 v2, v42, v2, s23
	s_waitcnt lgkmcnt(0)
	v_bfe_u32 v27, v44, 16, 1
	v_ashrrev_i32_e32 v47, 31, v46
	v_lshrrev_b32_e32 v2, 16, v2
	v_add3_u32 v27, v44, v27, s23
	v_lshlrev_b64 v[46:47], 11, v[46:47]
	v_and_or_b32 v27, v27, s24, v2
	v_lshl_add_u64 v[46:47], v[32:33], 0, v[46:47]
	v_bfe_u32 v2, v31, 16, 1
	global_store_dwordx4 v[46:47], v[24:27], off
	v_add3_u32 v2, v31, v2, s23
	v_lshrrev_b32_e32 v2, 16, v2
	v_bfe_u32 v24, v29, 16, 1
	v_add3_u32 v24, v29, v24, s23
	v_and_or_b32 v24, v24, s24, v2
	v_bfe_u32 v2, v35, 16, 1
	v_add3_u32 v2, v35, v2, s23
	v_bfe_u32 v25, v37, 16, 1
	v_lshrrev_b32_e32 v2, 16, v2
	v_add3_u32 v25, v37, v25, s23
	v_and_or_b32 v25, v25, s24, v2
	v_bfe_u32 v2, v39, 16, 1
	v_add3_u32 v2, v39, v2, s23
	v_bfe_u32 v26, v41, 16, 1
	v_lshrrev_b32_e32 v2, 16, v2
	v_add3_u32 v26, v41, v26, s23
	v_and_or_b32 v26, v26, s24, v2
	v_bfe_u32 v2, v43, 16, 1
	v_add_u32_e32 v28, s4, v56
	v_add3_u32 v2, v43, v2, s23
	v_bfe_u32 v27, v45, 16, 1
	v_ashrrev_i32_e32 v29, 31, v28
	v_lshrrev_b32_e32 v2, 16, v2
	v_add3_u32 v27, v45, v27, s23
	v_lshlrev_b64 v[28:29], 11, v[28:29]
	v_and_or_b32 v27, v27, s24, v2
	v_lshl_add_u64 v[28:29], v[32:33], 0, v[28:29]
	global_store_dwordx4 v[28:29], v[24:27], off
	s_waitcnt lgkmcnt(0)
	s_branch .LBB0_13
